# skinny GEMM (128 sample rows, 6 phases): K loop software-pipelined with 32 loads in flight instead of ~4.5 exposed round trips per 8 k-steps; on top of v6
# baseline (speedup 1.0000x reference)
.LBB0_339:
	v_add_co_u32_e32 v56, vcc, 0x100000, v16
	s_nop 1
	v_addc_co_u32_e32 v57, vcc, 0, v17, vcc
	v_add_co_u32_e32 v58, vcc, 0xbc11000, v14
	s_nop 1
	v_addc_co_u32_e32 v59, vcc, 0, v15, vcc
	global_load_dwordx4 v[24:27], v[56:57], off
	global_load_dwordx4 v[176:179], v[58:59], off
	global_load_dwordx4 v[28:31], v[56:57], off offset:64
	global_load_dwordx4 v[180:183], v[58:59], off offset:64
	global_load_dwordx4 v[32:35], v[56:57], off offset:128
	global_load_dwordx4 v[184:187], v[58:59], off offset:128
	global_load_dwordx4 v[36:39], v[56:57], off offset:192
	global_load_dwordx4 v[188:191], v[58:59], off offset:192
	global_load_dwordx4 v[40:43], v[56:57], off offset:256
	global_load_dwordx4 v[192:195], v[58:59], off offset:256
	global_load_dwordx4 v[44:47], v[56:57], off offset:320
	global_load_dwordx4 v[196:199], v[58:59], off offset:320
	global_load_dwordx4 v[48:51], v[56:57], off offset:384
	global_load_dwordx4 v[200:203], v[58:59], off offset:384
	global_load_dwordx4 v[52:55], v[56:57], off offset:448
	global_load_dwordx4 v[204:207], v[58:59], off offset:448
	global_load_dwordx4 v[132:135], v[56:57], off offset:512
	global_load_dwordx4 v[208:211], v[58:59], off offset:512
	global_load_dwordx4 v[136:139], v[56:57], off offset:576
	global_load_dwordx4 v[212:215], v[58:59], off offset:576
	global_load_dwordx4 v[140:143], v[56:57], off offset:640
	global_load_dwordx4 v[216:219], v[58:59], off offset:640
	global_load_dwordx4 v[148:151], v[56:57], off offset:704
	global_load_dwordx4 v[220:223], v[58:59], off offset:704
	global_load_dwordx4 v[152:155], v[56:57], off offset:768
	global_load_dwordx4 v[224:227], v[58:59], off offset:768
	global_load_dwordx4 v[156:159], v[56:57], off offset:832
	global_load_dwordx4 v[228:231], v[58:59], off offset:832
	global_load_dwordx4 v[168:171], v[56:57], off offset:896
	global_load_dwordx4 v[232:235], v[58:59], off offset:896
	global_load_dwordx4 v[172:175], v[56:57], off offset:960
	global_load_dwordx4 v[236:239], v[58:59], off offset:960
	s_waitcnt vmcnt(30)
	v_mfma_f32_16x16x32_bf16 v[2:5], v[24:27], v[176:179], v[2:5]
	global_load_dwordx4 v[24:27], v[56:57], off offset:1024
	global_load_dwordx4 v[176:179], v[58:59], off offset:1024
	s_waitcnt vmcnt(30)
	v_mfma_f32_16x16x32_bf16 v[2:5], v[28:31], v[180:183], v[2:5]
	global_load_dwordx4 v[28:31], v[56:57], off offset:1088
	global_load_dwordx4 v[180:183], v[58:59], off offset:1088
	s_waitcnt vmcnt(30)
	v_mfma_f32_16x16x32_bf16 v[2:5], v[32:35], v[184:187], v[2:5]
	global_load_dwordx4 v[32:35], v[56:57], off offset:1152
	global_load_dwordx4 v[184:187], v[58:59], off offset:1152
	s_waitcnt vmcnt(30)
	v_mfma_f32_16x16x32_bf16 v[2:5], v[36:39], v[188:191], v[2:5]
	global_load_dwordx4 v[36:39], v[56:57], off offset:1216
	global_load_dwordx4 v[188:191], v[58:59], off offset:1216
	s_waitcnt vmcnt(30)
	v_mfma_f32_16x16x32_bf16 v[2:5], v[40:43], v[192:195], v[2:5]
	global_load_dwordx4 v[40:43], v[56:57], off offset:1280
	global_load_dwordx4 v[192:195], v[58:59], off offset:1280
	s_waitcnt vmcnt(30)
	v_mfma_f32_16x16x32_bf16 v[2:5], v[44:47], v[196:199], v[2:5]
	global_load_dwordx4 v[44:47], v[56:57], off offset:1344
	global_load_dwordx4 v[196:199], v[58:59], off offset:1344
	s_waitcnt vmcnt(30)
	v_mfma_f32_16x16x32_bf16 v[2:5], v[48:51], v[200:203], v[2:5]
	global_load_dwordx4 v[48:51], v[56:57], off offset:1408
	global_load_dwordx4 v[200:203], v[58:59], off offset:1408
	s_waitcnt vmcnt(30)
	v_mfma_f32_16x16x32_bf16 v[2:5], v[52:55], v[204:207], v[2:5]
	global_load_dwordx4 v[52:55], v[56:57], off offset:1472
	global_load_dwordx4 v[204:207], v[58:59], off offset:1472
	s_waitcnt vmcnt(30)
	v_mfma_f32_16x16x32_bf16 v[2:5], v[132:135], v[208:211], v[2:5]
	global_load_dwordx4 v[132:135], v[56:57], off offset:1536
	global_load_dwordx4 v[208:211], v[58:59], off offset:1536
	s_waitcnt vmcnt(30)
	v_mfma_f32_16x16x32_bf16 v[2:5], v[136:139], v[212:215], v[2:5]
	global_load_dwordx4 v[136:139], v[56:57], off offset:1600
	global_load_dwordx4 v[212:215], v[58:59], off offset:1600
	s_waitcnt vmcnt(30)
	v_mfma_f32_16x16x32_bf16 v[2:5], v[140:143], v[216:219], v[2:5]
	global_load_dwordx4 v[140:143], v[56:57], off offset:1664
	global_load_dwordx4 v[216:219], v[58:59], off offset:1664
	s_waitcnt vmcnt(30)
	v_mfma_f32_16x16x32_bf16 v[2:5], v[148:151], v[220:223], v[2:5]
	global_load_dwordx4 v[148:151], v[56:57], off offset:1728
	global_load_dwordx4 v[220:223], v[58:59], off offset:1728
	s_waitcnt vmcnt(30)
	v_mfma_f32_16x16x32_bf16 v[2:5], v[152:155], v[224:227], v[2:5]
	global_load_dwordx4 v[152:155], v[56:57], off offset:1792
	global_load_dwordx4 v[224:227], v[58:59], off offset:1792
	s_waitcnt vmcnt(30)
	v_mfma_f32_16x16x32_bf16 v[2:5], v[156:159], v[228:231], v[2:5]
	global_load_dwordx4 v[156:159], v[56:57], off offset:1856
	global_load_dwordx4 v[228:231], v[58:59], off offset:1856
	s_waitcnt vmcnt(30)
	v_mfma_f32_16x16x32_bf16 v[2:5], v[168:171], v[232:235], v[2:5]
	global_load_dwordx4 v[168:171], v[56:57], off offset:1920
	global_load_dwordx4 v[232:235], v[58:59], off offset:1920
	s_waitcnt vmcnt(30)
	v_mfma_f32_16x16x32_bf16 v[2:5], v[172:175], v[236:239], v[2:5]
	global_load_dwordx4 v[172:175], v[56:57], off offset:1984
	global_load_dwordx4 v[236:239], v[58:59], off offset:1984
	s_waitcnt vmcnt(30)
	v_mfma_f32_16x16x32_bf16 v[2:5], v[24:27], v[176:179], v[2:5]
	s_waitcnt vmcnt(28)
	v_mfma_f32_16x16x32_bf16 v[2:5], v[28:31], v[180:183], v[2:5]
	s_waitcnt vmcnt(26)
	v_mfma_f32_16x16x32_bf16 v[2:5], v[32:35], v[184:187], v[2:5]
	s_waitcnt vmcnt(24)
	v_mfma_f32_16x16x32_bf16 v[2:5], v[36:39], v[188:191], v[2:5]
	s_waitcnt vmcnt(22)
	v_mfma_f32_16x16x32_bf16 v[2:5], v[40:43], v[192:195], v[2:5]
	s_waitcnt vmcnt(20)
	v_mfma_f32_16x16x32_bf16 v[2:5], v[44:47], v[196:199], v[2:5]
	s_waitcnt vmcnt(18)
	v_mfma_f32_16x16x32_bf16 v[2:5], v[48:51], v[200:203], v[2:5]
	s_waitcnt vmcnt(16)
	v_mfma_f32_16x16x32_bf16 v[2:5], v[52:55], v[204:207], v[2:5]
	s_waitcnt vmcnt(14)
	v_mfma_f32_16x16x32_bf16 v[2:5], v[132:135], v[208:211], v[2:5]
	s_waitcnt vmcnt(12)
	v_mfma_f32_16x16x32_bf16 v[2:5], v[136:139], v[212:215], v[2:5]
	s_waitcnt vmcnt(10)
	v_mfma_f32_16x16x32_bf16 v[2:5], v[140:143], v[216:219], v[2:5]
	s_waitcnt vmcnt(8)
	v_mfma_f32_16x16x32_bf16 v[2:5], v[148:151], v[220:223], v[2:5]
	s_waitcnt vmcnt(6)
	v_mfma_f32_16x16x32_bf16 v[2:5], v[152:155], v[224:227], v[2:5]
	s_waitcnt vmcnt(4)
	v_mfma_f32_16x16x32_bf16 v[2:5], v[156:159], v[228:231], v[2:5]
	s_waitcnt vmcnt(2)
	v_mfma_f32_16x16x32_bf16 v[2:5], v[168:171], v[232:235], v[2:5]
	s_waitcnt vmcnt(0)
	v_mfma_f32_16x16x32_bf16 v[2:5], v[172:175], v[236:239], v[2:5]
	s_movk_i32 s4, 0x800
	s_nop 1
	v_lshl_or_b32 v16, s8, 4, v18
	v_ashrrev_i32_e32 v17, 31, v16
	s_add_i32 s8, s8, s90
	s_nop 3
	v_cvt_pk_bf16_f32 v2, v2, v3
	v_cvt_pk_bf16_f32 v3, v4, v5
	v_lshl_add_u64 v[4:5], v[16:17], 1, v[8:9]
	s_cmpk_gt_i32 s8, 0xff
	v_add_u32_e32 v12, s3, v12
	global_store_dwordx2 v[4:5], v[2:3], off
	s_cbranch_scc0 .LBB0_338

.LBB0_982:
	v_add_co_u32_e32 v58, vcc, 0x900000, v18
	s_nop 1
	v_addc_co_u32_e32 v59, vcc, 0, v19, vcc
	v_add_co_u32_e32 v60, vcc, 0x26e13000, v16
	s_nop 1
	v_addc_co_u32_e32 v61, vcc, 0, v17, vcc
	global_load_dwordx4 v[26:29], v[58:59], off
	global_load_dwordx4 v[176:179], v[60:61], off
	global_load_dwordx4 v[30:33], v[58:59], off offset:64
	global_load_dwordx4 v[180:183], v[60:61], off offset:64
	global_load_dwordx4 v[34:37], v[58:59], off offset:128
	global_load_dwordx4 v[184:187], v[60:61], off offset:128
	global_load_dwordx4 v[38:41], v[58:59], off offset:192
	global_load_dwordx4 v[188:191], v[60:61], off offset:192
	global_load_dwordx4 v[42:45], v[58:59], off offset:256
	global_load_dwordx4 v[192:195], v[60:61], off offset:256
	global_load_dwordx4 v[46:49], v[58:59], off offset:320
	global_load_dwordx4 v[196:199], v[60:61], off offset:320
	global_load_dwordx4 v[50:53], v[58:59], off offset:384
	global_load_dwordx4 v[200:203], v[60:61], off offset:384
	global_load_dwordx4 v[54:57], v[58:59], off offset:448
	global_load_dwordx4 v[204:207], v[60:61], off offset:448
	global_load_dwordx4 v[132:135], v[58:59], off offset:512
	global_load_dwordx4 v[208:211], v[60:61], off offset:512
	global_load_dwordx4 v[136:139], v[58:59], off offset:576
	global_load_dwordx4 v[212:215], v[60:61], off offset:576
	global_load_dwordx4 v[140:143], v[58:59], off offset:640
	global_load_dwordx4 v[216:219], v[60:61], off offset:640
	global_load_dwordx4 v[148:151], v[58:59], off offset:704
	global_load_dwordx4 v[220:223], v[60:61], off offset:704
	global_load_dwordx4 v[152:155], v[58:59], off offset:768
	global_load_dwordx4 v[224:227], v[60:61], off offset:768
	global_load_dwordx4 v[156:159], v[58:59], off offset:832
	global_load_dwordx4 v[228:231], v[60:61], off offset:832
	global_load_dwordx4 v[168:171], v[58:59], off offset:896
	global_load_dwordx4 v[232:235], v[60:61], off offset:896
	global_load_dwordx4 v[172:175], v[58:59], off offset:960
	global_load_dwordx4 v[236:239], v[60:61], off offset:960
	s_waitcnt vmcnt(30)
	v_mfma_f32_16x16x32_bf16 v[2:5], v[26:29], v[176:179], v[2:5]
	global_load_dwordx4 v[26:29], v[58:59], off offset:1024
	global_load_dwordx4 v[176:179], v[60:61], off offset:1024
	s_waitcnt vmcnt(30)
	v_mfma_f32_16x16x32_bf16 v[2:5], v[30:33], v[180:183], v[2:5]
	global_load_dwordx4 v[30:33], v[58:59], off offset:1088
	global_load_dwordx4 v[180:183], v[60:61], off offset:1088
	s_waitcnt vmcnt(30)
	v_mfma_f32_16x16x32_bf16 v[2:5], v[34:37], v[184:187], v[2:5]
	global_load_dwordx4 v[34:37], v[58:59], off offset:1152
	global_load_dwordx4 v[184:187], v[60:61], off offset:1152
	s_waitcnt vmcnt(30)
	v_mfma_f32_16x16x32_bf16 v[2:5], v[38:41], v[188:191], v[2:5]
	global_load_dwordx4 v[38:41], v[58:59], off offset:1216
	global_load_dwordx4 v[188:191], v[60:61], off offset:1216
	s_waitcnt vmcnt(30)
	v_mfma_f32_16x16x32_bf16 v[2:5], v[42:45], v[192:195], v[2:5]
	global_load_dwordx4 v[42:45], v[58:59], off offset:1280
	global_load_dwordx4 v[192:195], v[60:61], off offset:1280
	s_waitcnt vmcnt(30)
	v_mfma_f32_16x16x32_bf16 v[2:5], v[46:49], v[196:199], v[2:5]
	global_load_dwordx4 v[46:49], v[58:59], off offset:1344
	global_load_dwordx4 v[196:199], v[60:61], off offset:1344
	s_waitcnt vmcnt(30)
	v_mfma_f32_16x16x32_bf16 v[2:5], v[50:53], v[200:203], v[2:5]
	global_load_dwordx4 v[50:53], v[58:59], off offset:1408
	global_load_dwordx4 v[200:203], v[60:61], off offset:1408
	s_waitcnt vmcnt(30)
	v_mfma_f32_16x16x32_bf16 v[2:5], v[54:57], v[204:207], v[2:5]
	global_load_dwordx4 v[54:57], v[58:59], off offset:1472
	global_load_dwordx4 v[204:207], v[60:61], off offset:1472
	s_waitcnt vmcnt(30)
	v_mfma_f32_16x16x32_bf16 v[2:5], v[132:135], v[208:211], v[2:5]
	global_load_dwordx4 v[132:135], v[58:59], off offset:1536
	global_load_dwordx4 v[208:211], v[60:61], off offset:1536
	s_waitcnt vmcnt(30)
	v_mfma_f32_16x16x32_bf16 v[2:5], v[136:139], v[212:215], v[2:5]
	global_load_dwordx4 v[136:139], v[58:59], off offset:1600
	global_load_dwordx4 v[212:215], v[60:61], off offset:1600
	s_waitcnt vmcnt(30)
	v_mfma_f32_16x16x32_bf16 v[2:5], v[140:143], v[216:219], v[2:5]
	global_load_dwordx4 v[140:143], v[58:59], off offset:1664
	global_load_dwordx4 v[216:219], v[60:61], off offset:1664
	s_waitcnt vmcnt(30)
	v_mfma_f32_16x16x32_bf16 v[2:5], v[148:151], v[220:223], v[2:5]
	global_load_dwordx4 v[148:151], v[58:59], off offset:1728
	global_load_dwordx4 v[220:223], v[60:61], off offset:1728
	s_waitcnt vmcnt(30)
	v_mfma_f32_16x16x32_bf16 v[2:5], v[152:155], v[224:227], v[2:5]
	global_load_dwordx4 v[152:155], v[58:59], off offset:1792
	global_load_dwordx4 v[224:227], v[60:61], off offset:1792
	s_waitcnt vmcnt(30)
	v_mfma_f32_16x16x32_bf16 v[2:5], v[156:159], v[228:231], v[2:5]
	global_load_dwordx4 v[156:159], v[58:59], off offset:1856
	global_load_dwordx4 v[228:231], v[60:61], off offset:1856
	s_waitcnt vmcnt(30)
	v_mfma_f32_16x16x32_bf16 v[2:5], v[168:171], v[232:235], v[2:5]
	global_load_dwordx4 v[168:171], v[58:59], off offset:1920
	global_load_dwordx4 v[232:235], v[60:61], off offset:1920
	s_waitcnt vmcnt(30)
	v_mfma_f32_16x16x32_bf16 v[2:5], v[172:175], v[236:239], v[2:5]
	global_load_dwordx4 v[172:175], v[58:59], off offset:1984
	global_load_dwordx4 v[236:239], v[60:61], off offset:1984
	s_waitcnt vmcnt(30)
	v_mfma_f32_16x16x32_bf16 v[2:5], v[26:29], v[176:179], v[2:5]
	s_waitcnt vmcnt(28)
	v_mfma_f32_16x16x32_bf16 v[2:5], v[30:33], v[180:183], v[2:5]
	s_waitcnt vmcnt(26)
	v_mfma_f32_16x16x32_bf16 v[2:5], v[34:37], v[184:187], v[2:5]
	s_waitcnt vmcnt(24)
	v_mfma_f32_16x16x32_bf16 v[2:5], v[38:41], v[188:191], v[2:5]
	s_waitcnt vmcnt(22)
	v_mfma_f32_16x16x32_bf16 v[2:5], v[42:45], v[192:195], v[2:5]
	s_waitcnt vmcnt(20)
	v_mfma_f32_16x16x32_bf16 v[2:5], v[46:49], v[196:199], v[2:5]
	s_waitcnt vmcnt(18)
	v_mfma_f32_16x16x32_bf16 v[2:5], v[50:53], v[200:203], v[2:5]
	s_waitcnt vmcnt(16)
	v_mfma_f32_16x16x32_bf16 v[2:5], v[54:57], v[204:207], v[2:5]
	s_waitcnt vmcnt(14)
	v_mfma_f32_16x16x32_bf16 v[2:5], v[132:135], v[208:211], v[2:5]
	s_waitcnt vmcnt(12)
	v_mfma_f32_16x16x32_bf16 v[2:5], v[136:139], v[212:215], v[2:5]
	s_waitcnt vmcnt(10)
	v_mfma_f32_16x16x32_bf16 v[2:5], v[140:143], v[216:219], v[2:5]
	s_waitcnt vmcnt(8)
	v_mfma_f32_16x16x32_bf16 v[2:5], v[148:151], v[220:223], v[2:5]
	s_waitcnt vmcnt(6)
	v_mfma_f32_16x16x32_bf16 v[2:5], v[152:155], v[224:227], v[2:5]
	s_waitcnt vmcnt(4)
	v_mfma_f32_16x16x32_bf16 v[2:5], v[156:159], v[228:231], v[2:5]
	s_waitcnt vmcnt(2)
	v_mfma_f32_16x16x32_bf16 v[2:5], v[168:171], v[232:235], v[2:5]
	s_waitcnt vmcnt(0)
	v_mfma_f32_16x16x32_bf16 v[2:5], v[172:175], v[236:239], v[2:5]
	s_movk_i32 s4, 0x800
	s_nop 1
	v_lshl_or_b32 v18, s8, 4, v20
	v_ashrrev_i32_e32 v19, 31, v18
	v_lshlrev_b64 v[18:19], 2, v[18:19]
	v_lshl_add_u64 v[22:23], v[10:11], 0, v[18:19]
	global_load_dwordx4 v[22:25], v[22:23], off
	s_add_i32 s8, s8, s90
	s_cmp_gt_i32 s8, 63
	v_lshl_add_u64 v[18:19], v[8:9], 0, v[18:19]
	v_add_u32_e32 v14, s3, v14
	s_waitcnt vmcnt(0)
	v_pk_add_f32 v[4:5], v[4:5], v[24:25]
	v_pk_add_f32 v[2:3], v[2:3], v[22:23]
	global_store_dwordx4 v[18:19], v[2:5], off
	s_cbranch_scc0 .LBB0_981

.LBB0_1110:
	v_add_co_u32_e32 v56, vcc, 0x1280000, v16
	s_nop 1
	v_addc_co_u32_e32 v57, vcc, 0, v17, vcc
	v_add_co_u32_e32 v58, vcc, 0xdc51000, v14
	s_nop 1
	v_addc_co_u32_e32 v59, vcc, 0, v15, vcc
	global_load_dwordx4 v[24:27], v[56:57], off
	global_load_dwordx4 v[176:179], v[58:59], off
	global_load_dwordx4 v[28:31], v[56:57], off offset:64
	global_load_dwordx4 v[180:183], v[58:59], off offset:64
	global_load_dwordx4 v[32:35], v[56:57], off offset:128
	global_load_dwordx4 v[184:187], v[58:59], off offset:128
	global_load_dwordx4 v[36:39], v[56:57], off offset:192
	global_load_dwordx4 v[188:191], v[58:59], off offset:192
	global_load_dwordx4 v[40:43], v[56:57], off offset:256
	global_load_dwordx4 v[192:195], v[58:59], off offset:256
	global_load_dwordx4 v[44:47], v[56:57], off offset:320
	global_load_dwordx4 v[196:199], v[58:59], off offset:320
	global_load_dwordx4 v[48:51], v[56:57], off offset:384
	global_load_dwordx4 v[200:203], v[58:59], off offset:384
	global_load_dwordx4 v[52:55], v[56:57], off offset:448
	global_load_dwordx4 v[204:207], v[58:59], off offset:448
	global_load_dwordx4 v[132:135], v[56:57], off offset:512
	global_load_dwordx4 v[208:211], v[58:59], off offset:512
	global_load_dwordx4 v[136:139], v[56:57], off offset:576
	global_load_dwordx4 v[212:215], v[58:59], off offset:576
	global_load_dwordx4 v[140:143], v[56:57], off offset:640
	global_load_dwordx4 v[216:219], v[58:59], off offset:640
	global_load_dwordx4 v[148:151], v[56:57], off offset:704
	global_load_dwordx4 v[220:223], v[58:59], off offset:704
	global_load_dwordx4 v[152:155], v[56:57], off offset:768
	global_load_dwordx4 v[224:227], v[58:59], off offset:768
	global_load_dwordx4 v[156:159], v[56:57], off offset:832
	global_load_dwordx4 v[228:231], v[58:59], off offset:832
	global_load_dwordx4 v[168:171], v[56:57], off offset:896
	global_load_dwordx4 v[232:235], v[58:59], off offset:896
	global_load_dwordx4 v[172:175], v[56:57], off offset:960
	global_load_dwordx4 v[236:239], v[58:59], off offset:960
	s_waitcnt vmcnt(30)
	v_mfma_f32_16x16x32_bf16 v[2:5], v[24:27], v[176:179], v[2:5]
	global_load_dwordx4 v[24:27], v[56:57], off offset:1024
	global_load_dwordx4 v[176:179], v[58:59], off offset:1024
	s_waitcnt vmcnt(30)
	v_mfma_f32_16x16x32_bf16 v[2:5], v[28:31], v[180:183], v[2:5]
	global_load_dwordx4 v[28:31], v[56:57], off offset:1088
	global_load_dwordx4 v[180:183], v[58:59], off offset:1088
	s_waitcnt vmcnt(30)
	v_mfma_f32_16x16x32_bf16 v[2:5], v[32:35], v[184:187], v[2:5]
	global_load_dwordx4 v[32:35], v[56:57], off offset:1152
	global_load_dwordx4 v[184:187], v[58:59], off offset:1152
	s_waitcnt vmcnt(30)
	v_mfma_f32_16x16x32_bf16 v[2:5], v[36:39], v[188:191], v[2:5]
	global_load_dwordx4 v[36:39], v[56:57], off offset:1216
	global_load_dwordx4 v[188:191], v[58:59], off offset:1216
	s_waitcnt vmcnt(30)
	v_mfma_f32_16x16x32_bf16 v[2:5], v[40:43], v[192:195], v[2:5]
	global_load_dwordx4 v[40:43], v[56:57], off offset:1280
	global_load_dwordx4 v[192:195], v[58:59], off offset:1280
	s_waitcnt vmcnt(30)
	v_mfma_f32_16x16x32_bf16 v[2:5], v[44:47], v[196:199], v[2:5]
	global_load_dwordx4 v[44:47], v[56:57], off offset:1344
	global_load_dwordx4 v[196:199], v[58:59], off offset:1344
	s_waitcnt vmcnt(30)
	v_mfma_f32_16x16x32_bf16 v[2:5], v[48:51], v[200:203], v[2:5]
	global_load_dwordx4 v[48:51], v[56:57], off offset:1408
	global_load_dwordx4 v[200:203], v[58:59], off offset:1408
	s_waitcnt vmcnt(30)
	v_mfma_f32_16x16x32_bf16 v[2:5], v[52:55], v[204:207], v[2:5]
	global_load_dwordx4 v[52:55], v[56:57], off offset:1472
	global_load_dwordx4 v[204:207], v[58:59], off offset:1472
	s_waitcnt vmcnt(30)
	v_mfma_f32_16x16x32_bf16 v[2:5], v[132:135], v[208:211], v[2:5]
	global_load_dwordx4 v[132:135], v[56:57], off offset:1536
	global_load_dwordx4 v[208:211], v[58:59], off offset:1536
	s_waitcnt vmcnt(30)
	v_mfma_f32_16x16x32_bf16 v[2:5], v[136:139], v[212:215], v[2:5]
	global_load_dwordx4 v[136:139], v[56:57], off offset:1600
	global_load_dwordx4 v[212:215], v[58:59], off offset:1600
	s_waitcnt vmcnt(30)
	v_mfma_f32_16x16x32_bf16 v[2:5], v[140:143], v[216:219], v[2:5]
	global_load_dwordx4 v[140:143], v[56:57], off offset:1664
	global_load_dwordx4 v[216:219], v[58:59], off offset:1664
	s_waitcnt vmcnt(30)
	v_mfma_f32_16x16x32_bf16 v[2:5], v[148:151], v[220:223], v[2:5]
	global_load_dwordx4 v[148:151], v[56:57], off offset:1728
	global_load_dwordx4 v[220:223], v[58:59], off offset:1728
	s_waitcnt vmcnt(30)
	v_mfma_f32_16x16x32_bf16 v[2:5], v[152:155], v[224:227], v[2:5]
	global_load_dwordx4 v[152:155], v[56:57], off offset:1792
	global_load_dwordx4 v[224:227], v[58:59], off offset:1792
	s_waitcnt vmcnt(30)
	v_mfma_f32_16x16x32_bf16 v[2:5], v[156:159], v[228:231], v[2:5]
	global_load_dwordx4 v[156:159], v[56:57], off offset:1856
	global_load_dwordx4 v[228:231], v[58:59], off offset:1856
	s_waitcnt vmcnt(30)
	v_mfma_f32_16x16x32_bf16 v[2:5], v[168:171], v[232:235], v[2:5]
	global_load_dwordx4 v[168:171], v[56:57], off offset:1920
	global_load_dwordx4 v[232:235], v[58:59], off offset:1920
	s_waitcnt vmcnt(30)
	v_mfma_f32_16x16x32_bf16 v[2:5], v[172:175], v[236:239], v[2:5]
	global_load_dwordx4 v[172:175], v[56:57], off offset:1984
	global_load_dwordx4 v[236:239], v[58:59], off offset:1984
	s_waitcnt vmcnt(30)
	v_mfma_f32_16x16x32_bf16 v[2:5], v[24:27], v[176:179], v[2:5]
	s_waitcnt vmcnt(28)
	v_mfma_f32_16x16x32_bf16 v[2:5], v[28:31], v[180:183], v[2:5]
	s_waitcnt vmcnt(26)
	v_mfma_f32_16x16x32_bf16 v[2:5], v[32:35], v[184:187], v[2:5]
	s_waitcnt vmcnt(24)
	v_mfma_f32_16x16x32_bf16 v[2:5], v[36:39], v[188:191], v[2:5]
	s_waitcnt vmcnt(22)
	v_mfma_f32_16x16x32_bf16 v[2:5], v[40:43], v[192:195], v[2:5]
	s_waitcnt vmcnt(20)
	v_mfma_f32_16x16x32_bf16 v[2:5], v[44:47], v[196:199], v[2:5]
	s_waitcnt vmcnt(18)
	v_mfma_f32_16x16x32_bf16 v[2:5], v[48:51], v[200:203], v[2:5]
	s_waitcnt vmcnt(16)
	v_mfma_f32_16x16x32_bf16 v[2:5], v[52:55], v[204:207], v[2:5]
	s_waitcnt vmcnt(14)
	v_mfma_f32_16x16x32_bf16 v[2:5], v[132:135], v[208:211], v[2:5]
	s_waitcnt vmcnt(12)
	v_mfma_f32_16x16x32_bf16 v[2:5], v[136:139], v[212:215], v[2:5]
	s_waitcnt vmcnt(10)
	v_mfma_f32_16x16x32_bf16 v[2:5], v[140:143], v[216:219], v[2:5]
	s_waitcnt vmcnt(8)
	v_mfma_f32_16x16x32_bf16 v[2:5], v[148:151], v[220:223], v[2:5]
	s_waitcnt vmcnt(6)
	v_mfma_f32_16x16x32_bf16 v[2:5], v[152:155], v[224:227], v[2:5]
	s_waitcnt vmcnt(4)
	v_mfma_f32_16x16x32_bf16 v[2:5], v[156:159], v[228:231], v[2:5]
	s_waitcnt vmcnt(2)
	v_mfma_f32_16x16x32_bf16 v[2:5], v[168:171], v[232:235], v[2:5]
	s_waitcnt vmcnt(0)
	v_mfma_f32_16x16x32_bf16 v[2:5], v[172:175], v[236:239], v[2:5]
	s_movk_i32 s4, 0x800
	s_nop 1
	v_lshl_or_b32 v16, s8, 4, v18
	v_ashrrev_i32_e32 v17, 31, v16
	s_add_i32 s8, s8, s90
	s_nop 3
	v_cvt_pk_bf16_f32 v2, v2, v3
	v_cvt_pk_bf16_f32 v3, v4, v5
	v_lshl_add_u64 v[4:5], v[16:17], 1, v[8:9]
	s_cmpk_gt_i32 s8, 0x7f
	v_add_u32_e32 v12, s3, v12
	global_store_dwordx2 v[4:5], v[2:3], off
	s_cbranch_scc0 .LBB0_1109

.LBB0_1464:
	v_add_co_u32_e32 v58, vcc, 0xb00000, v18
	s_nop 1
	v_addc_co_u32_e32 v59, vcc, 0, v19, vcc
	v_add_co_u32_e32 v60, vcc, 0xbc11000, v16
	s_nop 1
	v_addc_co_u32_e32 v61, vcc, 0, v17, vcc
	global_load_dwordx4 v[26:29], v[58:59], off
	global_load_dwordx4 v[176:179], v[60:61], off
	global_load_dwordx4 v[30:33], v[58:59], off offset:64
	global_load_dwordx4 v[180:183], v[60:61], off offset:64
	global_load_dwordx4 v[34:37], v[58:59], off offset:128
	global_load_dwordx4 v[184:187], v[60:61], off offset:128
	global_load_dwordx4 v[38:41], v[58:59], off offset:192
	global_load_dwordx4 v[188:191], v[60:61], off offset:192
	global_load_dwordx4 v[42:45], v[58:59], off offset:256
	global_load_dwordx4 v[192:195], v[60:61], off offset:256
	global_load_dwordx4 v[46:49], v[58:59], off offset:320
	global_load_dwordx4 v[196:199], v[60:61], off offset:320
	global_load_dwordx4 v[50:53], v[58:59], off offset:384
	global_load_dwordx4 v[200:203], v[60:61], off offset:384
	global_load_dwordx4 v[54:57], v[58:59], off offset:448
	global_load_dwordx4 v[204:207], v[60:61], off offset:448
	global_load_dwordx4 v[132:135], v[58:59], off offset:512
	global_load_dwordx4 v[208:211], v[60:61], off offset:512
	global_load_dwordx4 v[136:139], v[58:59], off offset:576
	global_load_dwordx4 v[212:215], v[60:61], off offset:576
	global_load_dwordx4 v[140:143], v[58:59], off offset:640
	global_load_dwordx4 v[216:219], v[60:61], off offset:640
	global_load_dwordx4 v[148:151], v[58:59], off offset:704
	global_load_dwordx4 v[220:223], v[60:61], off offset:704
	global_load_dwordx4 v[152:155], v[58:59], off offset:768
	global_load_dwordx4 v[224:227], v[60:61], off offset:768
	global_load_dwordx4 v[156:159], v[58:59], off offset:832
	global_load_dwordx4 v[228:231], v[60:61], off offset:832
	global_load_dwordx4 v[168:171], v[58:59], off offset:896
	global_load_dwordx4 v[232:235], v[60:61], off offset:896
	global_load_dwordx4 v[172:175], v[58:59], off offset:960
	global_load_dwordx4 v[236:239], v[60:61], off offset:960
	s_waitcnt vmcnt(30)
	v_mfma_f32_16x16x32_bf16 v[2:5], v[26:29], v[176:179], v[2:5]
	global_load_dwordx4 v[26:29], v[58:59], off offset:1024
	global_load_dwordx4 v[176:179], v[60:61], off offset:1024
	s_waitcnt vmcnt(30)
	v_mfma_f32_16x16x32_bf16 v[2:5], v[30:33], v[180:183], v[2:5]
	global_load_dwordx4 v[30:33], v[58:59], off offset:1088
	global_load_dwordx4 v[180:183], v[60:61], off offset:1088
	s_waitcnt vmcnt(30)
	v_mfma_f32_16x16x32_bf16 v[2:5], v[34:37], v[184:187], v[2:5]
	global_load_dwordx4 v[34:37], v[58:59], off offset:1152
	global_load_dwordx4 v[184:187], v[60:61], off offset:1152
	s_waitcnt vmcnt(30)
	v_mfma_f32_16x16x32_bf16 v[2:5], v[38:41], v[188:191], v[2:5]
	global_load_dwordx4 v[38:41], v[58:59], off offset:1216
	global_load_dwordx4 v[188:191], v[60:61], off offset:1216
	s_waitcnt vmcnt(30)
	v_mfma_f32_16x16x32_bf16 v[2:5], v[42:45], v[192:195], v[2:5]
	global_load_dwordx4 v[42:45], v[58:59], off offset:1280
	global_load_dwordx4 v[192:195], v[60:61], off offset:1280
	s_waitcnt vmcnt(30)
	v_mfma_f32_16x16x32_bf16 v[2:5], v[46:49], v[196:199], v[2:5]
	global_load_dwordx4 v[46:49], v[58:59], off offset:1344
	global_load_dwordx4 v[196:199], v[60:61], off offset:1344
	s_waitcnt vmcnt(30)
	v_mfma_f32_16x16x32_bf16 v[2:5], v[50:53], v[200:203], v[2:5]
	global_load_dwordx4 v[50:53], v[58:59], off offset:1408
	global_load_dwordx4 v[200:203], v[60:61], off offset:1408
	s_waitcnt vmcnt(30)
	v_mfma_f32_16x16x32_bf16 v[2:5], v[54:57], v[204:207], v[2:5]
	global_load_dwordx4 v[54:57], v[58:59], off offset:1472
	global_load_dwordx4 v[204:207], v[60:61], off offset:1472
	s_waitcnt vmcnt(30)
	v_mfma_f32_16x16x32_bf16 v[2:5], v[132:135], v[208:211], v[2:5]
	global_load_dwordx4 v[132:135], v[58:59], off offset:1536
	global_load_dwordx4 v[208:211], v[60:61], off offset:1536
	s_waitcnt vmcnt(30)
	v_mfma_f32_16x16x32_bf16 v[2:5], v[136:139], v[212:215], v[2:5]
	global_load_dwordx4 v[136:139], v[58:59], off offset:1600
	global_load_dwordx4 v[212:215], v[60:61], off offset:1600
	s_waitcnt vmcnt(30)
	v_mfma_f32_16x16x32_bf16 v[2:5], v[140:143], v[216:219], v[2:5]
	global_load_dwordx4 v[140:143], v[58:59], off offset:1664
	global_load_dwordx4 v[216:219], v[60:61], off offset:1664
	s_waitcnt vmcnt(30)
	v_mfma_f32_16x16x32_bf16 v[2:5], v[148:151], v[220:223], v[2:5]
	global_load_dwordx4 v[148:151], v[58:59], off offset:1728
	global_load_dwordx4 v[220:223], v[60:61], off offset:1728
	s_waitcnt vmcnt(30)
	v_mfma_f32_16x16x32_bf16 v[2:5], v[152:155], v[224:227], v[2:5]
	global_load_dwordx4 v[152:155], v[58:59], off offset:1792
	global_load_dwordx4 v[224:227], v[60:61], off offset:1792
	s_waitcnt vmcnt(30)
	v_mfma_f32_16x16x32_bf16 v[2:5], v[156:159], v[228:231], v[2:5]
	global_load_dwordx4 v[156:159], v[58:59], off offset:1856
	global_load_dwordx4 v[228:231], v[60:61], off offset:1856
	s_waitcnt vmcnt(30)
	v_mfma_f32_16x16x32_bf16 v[2:5], v[168:171], v[232:235], v[2:5]
	global_load_dwordx4 v[168:171], v[58:59], off offset:1920
	global_load_dwordx4 v[232:235], v[60:61], off offset:1920
	s_waitcnt vmcnt(30)
	v_mfma_f32_16x16x32_bf16 v[2:5], v[172:175], v[236:239], v[2:5]
	global_load_dwordx4 v[172:175], v[58:59], off offset:1984
	global_load_dwordx4 v[236:239], v[60:61], off offset:1984
	s_waitcnt vmcnt(30)
	v_mfma_f32_16x16x32_bf16 v[2:5], v[26:29], v[176:179], v[2:5]
	s_waitcnt vmcnt(28)
	v_mfma_f32_16x16x32_bf16 v[2:5], v[30:33], v[180:183], v[2:5]
	s_waitcnt vmcnt(26)
	v_mfma_f32_16x16x32_bf16 v[2:5], v[34:37], v[184:187], v[2:5]
	s_waitcnt vmcnt(24)
	v_mfma_f32_16x16x32_bf16 v[2:5], v[38:41], v[188:191], v[2:5]
	s_waitcnt vmcnt(22)
	v_mfma_f32_16x16x32_bf16 v[2:5], v[42:45], v[192:195], v[2:5]
	s_waitcnt vmcnt(20)
	v_mfma_f32_16x16x32_bf16 v[2:5], v[46:49], v[196:199], v[2:5]
	s_waitcnt vmcnt(18)
	v_mfma_f32_16x16x32_bf16 v[2:5], v[50:53], v[200:203], v[2:5]
	s_waitcnt vmcnt(16)
	v_mfma_f32_16x16x32_bf16 v[2:5], v[54:57], v[204:207], v[2:5]
	s_waitcnt vmcnt(14)
	v_mfma_f32_16x16x32_bf16 v[2:5], v[132:135], v[208:211], v[2:5]
	s_waitcnt vmcnt(12)
	v_mfma_f32_16x16x32_bf16 v[2:5], v[136:139], v[212:215], v[2:5]
	s_waitcnt vmcnt(10)
	v_mfma_f32_16x16x32_bf16 v[2:5], v[140:143], v[216:219], v[2:5]
	s_waitcnt vmcnt(8)
	v_mfma_f32_16x16x32_bf16 v[2:5], v[148:151], v[220:223], v[2:5]
	s_waitcnt vmcnt(6)
	v_mfma_f32_16x16x32_bf16 v[2:5], v[152:155], v[224:227], v[2:5]
	s_waitcnt vmcnt(4)
	v_mfma_f32_16x16x32_bf16 v[2:5], v[156:159], v[228:231], v[2:5]
	s_waitcnt vmcnt(2)
	v_mfma_f32_16x16x32_bf16 v[2:5], v[168:171], v[232:235], v[2:5]
	s_waitcnt vmcnt(0)
	v_mfma_f32_16x16x32_bf16 v[2:5], v[172:175], v[236:239], v[2:5]
	s_movk_i32 s4, 0x800
	s_nop 1
	v_lshl_or_b32 v18, s7, 4, v20
	v_cmp_gt_i32_e32 vcc, s6, v18
	s_and_saveexec_b64 s[4:5], vcc
	s_cbranch_execz .LBB0_1462
	global_load_dwordx4 v[22:25], v[8:9], off
	global_load_dwordx4 v[26:29], v[8:9], off offset:16
	v_ashrrev_i32_e32 v19, 31, v18
	s_waitcnt vmcnt(1)
	v_mov_b32_e32 v30, v22
	s_waitcnt vmcnt(0)
	v_mov_b32_e32 v31, v26
	v_mov_b32_e32 v26, v23
	v_mov_b32_e32 v22, v24
	v_mov_b32_e32 v23, v28
	v_mov_b32_e32 v28, v25
	v_pk_add_f32 v[24:25], v[30:31], v[26:27]
	v_pk_add_f32 v[22:23], v[22:23], v[28:29]
	s_nop 0
	v_pk_add_f32 v[22:23], v[24:25], v[22:23]
	s_nop 0
	v_add_f32_e32 v6, v22, v23
	v_fmamk_f32 v6, v6, 0x3a800000, v1
	v_rsq_f32_e32 v6, v6
	s_nop 0
	v_pk_mul_f32 v[4:5], v[4:5], v[6:7] op_sel_hi:[1,0]
	v_pk_mul_f32 v[2:3], v[2:3], v[6:7] op_sel_hi:[1,0]
	s_nop 0
	v_cvt_pk_bf16_f32 v2, v2, v3
	v_cvt_pk_bf16_f32 v3, v4, v5
	v_lshl_add_u64 v[4:5], v[18:19], 1, v[10:11]
	global_store_dwordx2 v[4:5], v[2:3], off
	s_branch .LBB0_1462

.LBB0_3207:
	v_add_co_u32_e32 v58, vcc, 0x1080000, v18
	s_nop 1
	v_addc_co_u32_e32 v59, vcc, 0, v19, vcc
	v_add_co_u32_e32 v60, vcc, 0x26e13000, v16
	s_nop 1
	v_addc_co_u32_e32 v61, vcc, 0, v17, vcc
	global_load_dwordx4 v[26:29], v[58:59], off
	global_load_dwordx4 v[94:97], v[60:61], off
	global_load_dwordx4 v[30:33], v[58:59], off offset:64
	global_load_dwordx4 v[98:101], v[60:61], off offset:64
	global_load_dwordx4 v[34:37], v[58:59], off offset:128
	global_load_dwordx4 v[102:105], v[60:61], off offset:128
	global_load_dwordx4 v[38:41], v[58:59], off offset:192
	global_load_dwordx4 v[106:109], v[60:61], off offset:192
	global_load_dwordx4 v[42:45], v[58:59], off offset:256
	global_load_dwordx4 v[110:113], v[60:61], off offset:256
	global_load_dwordx4 v[46:49], v[58:59], off offset:320
	global_load_dwordx4 v[114:117], v[60:61], off offset:320
	global_load_dwordx4 v[50:53], v[58:59], off offset:384
	global_load_dwordx4 v[118:121], v[60:61], off offset:384
	global_load_dwordx4 v[54:57], v[58:59], off offset:448
	global_load_dwordx4 v[122:125], v[60:61], off offset:448
	global_load_dwordx4 v[62:65], v[58:59], off offset:512
	global_load_dwordx4 v[126:129], v[60:61], off offset:512
	global_load_dwordx4 v[66:69], v[58:59], off offset:576
	global_load_dwordx4 v[130:133], v[60:61], off offset:576
	global_load_dwordx4 v[70:73], v[58:59], off offset:640
	global_load_dwordx4 v[134:137], v[60:61], off offset:640
	global_load_dwordx4 v[74:77], v[58:59], off offset:704
	global_load_dwordx4 v[138:141], v[60:61], off offset:704
	global_load_dwordx4 v[78:81], v[58:59], off offset:768
	global_load_dwordx4 v[142:145], v[60:61], off offset:768
	global_load_dwordx4 v[82:85], v[58:59], off offset:832
	global_load_dwordx4 v[148:151], v[60:61], off offset:832
	global_load_dwordx4 v[86:89], v[58:59], off offset:896
	global_load_dwordx4 v[152:155], v[60:61], off offset:896
	global_load_dwordx4 v[90:93], v[58:59], off offset:960
	global_load_dwordx4 v[156:159], v[60:61], off offset:960
	s_waitcnt vmcnt(30)
	v_mfma_f32_16x16x32_bf16 v[2:5], v[26:29], v[94:97], v[2:5]
	global_load_dwordx4 v[26:29], v[58:59], off offset:1024
	global_load_dwordx4 v[94:97], v[60:61], off offset:1024
	s_waitcnt vmcnt(30)
	v_mfma_f32_16x16x32_bf16 v[2:5], v[30:33], v[98:101], v[2:5]
	global_load_dwordx4 v[30:33], v[58:59], off offset:1088
	global_load_dwordx4 v[98:101], v[60:61], off offset:1088
	s_waitcnt vmcnt(30)
	v_mfma_f32_16x16x32_bf16 v[2:5], v[34:37], v[102:105], v[2:5]
	global_load_dwordx4 v[34:37], v[58:59], off offset:1152
	global_load_dwordx4 v[102:105], v[60:61], off offset:1152
	s_waitcnt vmcnt(30)
	v_mfma_f32_16x16x32_bf16 v[2:5], v[38:41], v[106:109], v[2:5]
	global_load_dwordx4 v[38:41], v[58:59], off offset:1216
	global_load_dwordx4 v[106:109], v[60:61], off offset:1216
	s_waitcnt vmcnt(30)
	v_mfma_f32_16x16x32_bf16 v[2:5], v[42:45], v[110:113], v[2:5]
	global_load_dwordx4 v[42:45], v[58:59], off offset:1280
	global_load_dwordx4 v[110:113], v[60:61], off offset:1280
	s_waitcnt vmcnt(30)
	v_mfma_f32_16x16x32_bf16 v[2:5], v[46:49], v[114:117], v[2:5]
	global_load_dwordx4 v[46:49], v[58:59], off offset:1344
	global_load_dwordx4 v[114:117], v[60:61], off offset:1344
	s_waitcnt vmcnt(30)
	v_mfma_f32_16x16x32_bf16 v[2:5], v[50:53], v[118:121], v[2:5]
	global_load_dwordx4 v[50:53], v[58:59], off offset:1408
	global_load_dwordx4 v[118:121], v[60:61], off offset:1408
	s_waitcnt vmcnt(30)
	v_mfma_f32_16x16x32_bf16 v[2:5], v[54:57], v[122:125], v[2:5]
	global_load_dwordx4 v[54:57], v[58:59], off offset:1472
	global_load_dwordx4 v[122:125], v[60:61], off offset:1472
	s_waitcnt vmcnt(30)
	v_mfma_f32_16x16x32_bf16 v[2:5], v[62:65], v[126:129], v[2:5]
	global_load_dwordx4 v[62:65], v[58:59], off offset:1536
	global_load_dwordx4 v[126:129], v[60:61], off offset:1536
	s_waitcnt vmcnt(30)
	v_mfma_f32_16x16x32_bf16 v[2:5], v[66:69], v[130:133], v[2:5]
	global_load_dwordx4 v[66:69], v[58:59], off offset:1600
	global_load_dwordx4 v[130:133], v[60:61], off offset:1600
	s_waitcnt vmcnt(30)
	v_mfma_f32_16x16x32_bf16 v[2:5], v[70:73], v[134:137], v[2:5]
	global_load_dwordx4 v[70:73], v[58:59], off offset:1664
	global_load_dwordx4 v[134:137], v[60:61], off offset:1664
	s_waitcnt vmcnt(30)
	v_mfma_f32_16x16x32_bf16 v[2:5], v[74:77], v[138:141], v[2:5]
	global_load_dwordx4 v[74:77], v[58:59], off offset:1728
	global_load_dwordx4 v[138:141], v[60:61], off offset:1728
	s_waitcnt vmcnt(30)
	v_mfma_f32_16x16x32_bf16 v[2:5], v[78:81], v[142:145], v[2:5]
	global_load_dwordx4 v[78:81], v[58:59], off offset:1792
	global_load_dwordx4 v[142:145], v[60:61], off offset:1792
	s_waitcnt vmcnt(30)
	v_mfma_f32_16x16x32_bf16 v[2:5], v[82:85], v[148:151], v[2:5]
	global_load_dwordx4 v[82:85], v[58:59], off offset:1856
	global_load_dwordx4 v[148:151], v[60:61], off offset:1856
	s_waitcnt vmcnt(30)
	v_mfma_f32_16x16x32_bf16 v[2:5], v[86:89], v[152:155], v[2:5]
	global_load_dwordx4 v[86:89], v[58:59], off offset:1920
	global_load_dwordx4 v[152:155], v[60:61], off offset:1920
	s_waitcnt vmcnt(30)
	v_mfma_f32_16x16x32_bf16 v[2:5], v[90:93], v[156:159], v[2:5]
	global_load_dwordx4 v[90:93], v[58:59], off offset:1984
	global_load_dwordx4 v[156:159], v[60:61], off offset:1984
	s_waitcnt vmcnt(30)
	v_mfma_f32_16x16x32_bf16 v[2:5], v[26:29], v[94:97], v[2:5]
	s_waitcnt vmcnt(28)
	v_mfma_f32_16x16x32_bf16 v[2:5], v[30:33], v[98:101], v[2:5]
	s_waitcnt vmcnt(26)
	v_mfma_f32_16x16x32_bf16 v[2:5], v[34:37], v[102:105], v[2:5]
	s_waitcnt vmcnt(24)
	v_mfma_f32_16x16x32_bf16 v[2:5], v[38:41], v[106:109], v[2:5]
	s_waitcnt vmcnt(22)
	v_mfma_f32_16x16x32_bf16 v[2:5], v[42:45], v[110:113], v[2:5]
	s_waitcnt vmcnt(20)
	v_mfma_f32_16x16x32_bf16 v[2:5], v[46:49], v[114:117], v[2:5]
	s_waitcnt vmcnt(18)
	v_mfma_f32_16x16x32_bf16 v[2:5], v[50:53], v[118:121], v[2:5]
	s_waitcnt vmcnt(16)
	v_mfma_f32_16x16x32_bf16 v[2:5], v[54:57], v[122:125], v[2:5]
	s_waitcnt vmcnt(14)
	v_mfma_f32_16x16x32_bf16 v[2:5], v[62:65], v[126:129], v[2:5]
	s_waitcnt vmcnt(12)
	v_mfma_f32_16x16x32_bf16 v[2:5], v[66:69], v[130:133], v[2:5]
	s_waitcnt vmcnt(10)
	v_mfma_f32_16x16x32_bf16 v[2:5], v[70:73], v[134:137], v[2:5]
	s_waitcnt vmcnt(8)
	v_mfma_f32_16x16x32_bf16 v[2:5], v[74:77], v[138:141], v[2:5]
	s_waitcnt vmcnt(6)
	v_mfma_f32_16x16x32_bf16 v[2:5], v[78:81], v[142:145], v[2:5]
	s_waitcnt vmcnt(4)
	v_mfma_f32_16x16x32_bf16 v[2:5], v[82:85], v[148:151], v[2:5]
	s_waitcnt vmcnt(2)
	v_mfma_f32_16x16x32_bf16 v[2:5], v[86:89], v[152:155], v[2:5]
	s_waitcnt vmcnt(0)
	v_mfma_f32_16x16x32_bf16 v[2:5], v[90:93], v[156:159], v[2:5]
	s_movk_i32 s0, 0x800
	s_nop 1
	v_lshl_or_b32 v18, s6, 4, v20
	v_ashrrev_i32_e32 v19, 31, v18
	v_lshlrev_b64 v[18:19], 2, v[18:19]
	v_lshl_add_u64 v[22:23], v[8:9], 0, v[18:19]
	global_load_dwordx4 v[22:25], v[22:23], off
	s_add_i32 s6, s6, s90
	s_cmp_gt_i32 s6, 63
	v_lshl_add_u64 v[18:19], v[10:11], 0, v[18:19]
	v_add_u32_e32 v14, s3, v14
	s_waitcnt vmcnt(0)
	v_pk_add_f32 v[4:5], v[4:5], v[24:25]
	v_pk_add_f32 v[2:3], v[2:3], v[22:23]
	global_store_dwordx4 v[18:19], v[2:5], off
	s_cbranch_scc0 .LBB0_3206

.LBB0_3335:
	v_add_co_u32_e32 v56, vcc, 0x1680000, v16
	s_nop 1
	v_addc_co_u32_e32 v57, vcc, 0, v17, vcc
	v_add_co_u32_e32 v58, vcc, 0xdc51000, v14
	s_nop 1
	v_addc_co_u32_e32 v59, vcc, 0, v15, vcc
	global_load_dwordx4 v[24:27], v[56:57], off
	global_load_dwordx4 v[92:95], v[58:59], off
	global_load_dwordx4 v[28:31], v[56:57], off offset:64
	global_load_dwordx4 v[96:99], v[58:59], off offset:64
	global_load_dwordx4 v[32:35], v[56:57], off offset:128
	global_load_dwordx4 v[100:103], v[58:59], off offset:128
	global_load_dwordx4 v[36:39], v[56:57], off offset:192
	global_load_dwordx4 v[104:107], v[58:59], off offset:192
	global_load_dwordx4 v[40:43], v[56:57], off offset:256
	global_load_dwordx4 v[108:111], v[58:59], off offset:256
	global_load_dwordx4 v[44:47], v[56:57], off offset:320
	global_load_dwordx4 v[112:115], v[58:59], off offset:320
	global_load_dwordx4 v[48:51], v[56:57], off offset:384
	global_load_dwordx4 v[116:119], v[58:59], off offset:384
	global_load_dwordx4 v[52:55], v[56:57], off offset:448
	global_load_dwordx4 v[120:123], v[58:59], off offset:448
	global_load_dwordx4 v[60:63], v[56:57], off offset:512
	global_load_dwordx4 v[124:127], v[58:59], off offset:512
	global_load_dwordx4 v[64:67], v[56:57], off offset:576
	global_load_dwordx4 v[128:131], v[58:59], off offset:576
	global_load_dwordx4 v[68:71], v[56:57], off offset:640
	global_load_dwordx4 v[132:135], v[58:59], off offset:640
	global_load_dwordx4 v[72:75], v[56:57], off offset:704
	global_load_dwordx4 v[136:139], v[58:59], off offset:704
	global_load_dwordx4 v[76:79], v[56:57], off offset:768
	global_load_dwordx4 v[140:143], v[58:59], off offset:768
	global_load_dwordx4 v[80:83], v[56:57], off offset:832
	global_load_dwordx4 v[148:151], v[58:59], off offset:832
	global_load_dwordx4 v[84:87], v[56:57], off offset:896
	global_load_dwordx4 v[152:155], v[58:59], off offset:896
	global_load_dwordx4 v[88:91], v[56:57], off offset:960
	global_load_dwordx4 v[156:159], v[58:59], off offset:960
	s_waitcnt vmcnt(30)
	v_mfma_f32_16x16x32_bf16 v[2:5], v[24:27], v[92:95], v[2:5]
	global_load_dwordx4 v[24:27], v[56:57], off offset:1024
	global_load_dwordx4 v[92:95], v[58:59], off offset:1024
	s_waitcnt vmcnt(30)
	v_mfma_f32_16x16x32_bf16 v[2:5], v[28:31], v[96:99], v[2:5]
	global_load_dwordx4 v[28:31], v[56:57], off offset:1088
	global_load_dwordx4 v[96:99], v[58:59], off offset:1088
	s_waitcnt vmcnt(30)
	v_mfma_f32_16x16x32_bf16 v[2:5], v[32:35], v[100:103], v[2:5]
	global_load_dwordx4 v[32:35], v[56:57], off offset:1152
	global_load_dwordx4 v[100:103], v[58:59], off offset:1152
	s_waitcnt vmcnt(30)
	v_mfma_f32_16x16x32_bf16 v[2:5], v[36:39], v[104:107], v[2:5]
	global_load_dwordx4 v[36:39], v[56:57], off offset:1216
	global_load_dwordx4 v[104:107], v[58:59], off offset:1216
	s_waitcnt vmcnt(30)
	v_mfma_f32_16x16x32_bf16 v[2:5], v[40:43], v[108:111], v[2:5]
	global_load_dwordx4 v[40:43], v[56:57], off offset:1280
	global_load_dwordx4 v[108:111], v[58:59], off offset:1280
	s_waitcnt vmcnt(30)
	v_mfma_f32_16x16x32_bf16 v[2:5], v[44:47], v[112:115], v[2:5]
	global_load_dwordx4 v[44:47], v[56:57], off offset:1344
	global_load_dwordx4 v[112:115], v[58:59], off offset:1344
	s_waitcnt vmcnt(30)
	v_mfma_f32_16x16x32_bf16 v[2:5], v[48:51], v[116:119], v[2:5]
	global_load_dwordx4 v[48:51], v[56:57], off offset:1408
	global_load_dwordx4 v[116:119], v[58:59], off offset:1408
	s_waitcnt vmcnt(30)
	v_mfma_f32_16x16x32_bf16 v[2:5], v[52:55], v[120:123], v[2:5]
	global_load_dwordx4 v[52:55], v[56:57], off offset:1472
	global_load_dwordx4 v[120:123], v[58:59], off offset:1472
	s_waitcnt vmcnt(30)
	v_mfma_f32_16x16x32_bf16 v[2:5], v[60:63], v[124:127], v[2:5]
	global_load_dwordx4 v[60:63], v[56:57], off offset:1536
	global_load_dwordx4 v[124:127], v[58:59], off offset:1536
	s_waitcnt vmcnt(30)
	v_mfma_f32_16x16x32_bf16 v[2:5], v[64:67], v[128:131], v[2:5]
	global_load_dwordx4 v[64:67], v[56:57], off offset:1600
	global_load_dwordx4 v[128:131], v[58:59], off offset:1600
	s_waitcnt vmcnt(30)
	v_mfma_f32_16x16x32_bf16 v[2:5], v[68:71], v[132:135], v[2:5]
	global_load_dwordx4 v[68:71], v[56:57], off offset:1664
	global_load_dwordx4 v[132:135], v[58:59], off offset:1664
	s_waitcnt vmcnt(30)
	v_mfma_f32_16x16x32_bf16 v[2:5], v[72:75], v[136:139], v[2:5]
	global_load_dwordx4 v[72:75], v[56:57], off offset:1728
	global_load_dwordx4 v[136:139], v[58:59], off offset:1728
	s_waitcnt vmcnt(30)
	v_mfma_f32_16x16x32_bf16 v[2:5], v[76:79], v[140:143], v[2:5]
	global_load_dwordx4 v[76:79], v[56:57], off offset:1792
	global_load_dwordx4 v[140:143], v[58:59], off offset:1792
	s_waitcnt vmcnt(30)
	v_mfma_f32_16x16x32_bf16 v[2:5], v[80:83], v[148:151], v[2:5]
	global_load_dwordx4 v[80:83], v[56:57], off offset:1856
	global_load_dwordx4 v[148:151], v[58:59], off offset:1856
	s_waitcnt vmcnt(30)
	v_mfma_f32_16x16x32_bf16 v[2:5], v[84:87], v[152:155], v[2:5]
	global_load_dwordx4 v[84:87], v[56:57], off offset:1920
	global_load_dwordx4 v[152:155], v[58:59], off offset:1920
	s_waitcnt vmcnt(30)
	v_mfma_f32_16x16x32_bf16 v[2:5], v[88:91], v[156:159], v[2:5]
	global_load_dwordx4 v[88:91], v[56:57], off offset:1984
	global_load_dwordx4 v[156:159], v[58:59], off offset:1984
	s_waitcnt vmcnt(30)
	v_mfma_f32_16x16x32_bf16 v[2:5], v[24:27], v[92:95], v[2:5]
	s_waitcnt vmcnt(28)
	v_mfma_f32_16x16x32_bf16 v[2:5], v[28:31], v[96:99], v[2:5]
	s_waitcnt vmcnt(26)
	v_mfma_f32_16x16x32_bf16 v[2:5], v[32:35], v[100:103], v[2:5]
	s_waitcnt vmcnt(24)
	v_mfma_f32_16x16x32_bf16 v[2:5], v[36:39], v[104:107], v[2:5]
	s_waitcnt vmcnt(22)
	v_mfma_f32_16x16x32_bf16 v[2:5], v[40:43], v[108:111], v[2:5]
	s_waitcnt vmcnt(20)
	v_mfma_f32_16x16x32_bf16 v[2:5], v[44:47], v[112:115], v[2:5]
	s_waitcnt vmcnt(18)
	v_mfma_f32_16x16x32_bf16 v[2:5], v[48:51], v[116:119], v[2:5]
	s_waitcnt vmcnt(16)
	v_mfma_f32_16x16x32_bf16 v[2:5], v[52:55], v[120:123], v[2:5]
	s_waitcnt vmcnt(14)
	v_mfma_f32_16x16x32_bf16 v[2:5], v[60:63], v[124:127], v[2:5]
	s_waitcnt vmcnt(12)
	v_mfma_f32_16x16x32_bf16 v[2:5], v[64:67], v[128:131], v[2:5]
	s_waitcnt vmcnt(10)
	v_mfma_f32_16x16x32_bf16 v[2:5], v[68:71], v[132:135], v[2:5]
	s_waitcnt vmcnt(8)
	v_mfma_f32_16x16x32_bf16 v[2:5], v[72:75], v[136:139], v[2:5]
	s_waitcnt vmcnt(6)
	v_mfma_f32_16x16x32_bf16 v[2:5], v[76:79], v[140:143], v[2:5]
	s_waitcnt vmcnt(4)
	v_mfma_f32_16x16x32_bf16 v[2:5], v[80:83], v[148:151], v[2:5]
	s_waitcnt vmcnt(2)
	v_mfma_f32_16x16x32_bf16 v[2:5], v[84:87], v[152:155], v[2:5]
	s_waitcnt vmcnt(0)
	v_mfma_f32_16x16x32_bf16 v[2:5], v[88:91], v[156:159], v[2:5]
	s_movk_i32 s0, 0x800
	s_nop 1
	v_lshl_or_b32 v16, s6, 4, v18
	v_ashrrev_i32_e32 v17, 31, v16
	s_add_i32 s6, s6, s90
	s_nop 3
	v_cvt_pk_bf16_f32 v2, v2, v3
	v_cvt_pk_bf16_f32 v3, v4, v5
	v_lshl_add_u64 v[4:5], v[16:17], 1, v[8:9]
	s_cmpk_gt_i32 s6, 0x7f
	v_add_u32_e32 v12, s3, v12
	global_store_dwordx2 v[4:5], v[2:3], off
	s_cbranch_scc0 .LBB0_3334
